# v23: P3 mid() gate-tile loads prefetched 8 chunks deep (counted vmcnt) + P11 epilogue base loads pipelined, on top of v21
# speedup vs baseline: 1.0143x; 1.0117x over previous
;     __device__ __forceinline__ void mid(f32x4 (&acc)[2][2][4][2], const Unit& u, int wr, int wc, int fr, int fq) const {
;         int row0 = u.pm * 256 + wr * 64 + fr; const int col0 = u.pn * 256 + wc * 32 + 8 * fq;
;         asm volatile("" : "+v"(row0));
; #pragma unroll
;         for (int ai = 0; ai < 2; ++ai)
; #pragma unroll
;             for (int m = 0; m < 4; ++m) {
;                 asm volatile("" ::: "memory");
;                 const size_t off = (size_t)(row0 + ai * 128 + m * 16) * D + col0;
; #pragma unroll
;                 for (int bj = 0; bj < 2; ++bj) {
;                     const u32x4 r = *(const u32x4*)(GR + off + bj * 128), g = *(const u32x4*)(GA + off + bj * 128);
;                     const f32x4 r0 = (f32x4){bflo(r.x), bfhi(r.x), bflo(r.y), bfhi(r.y)}, r1 = (f32x4){bflo(r.z), bfhi(r.z), bflo(r.w), bfhi(r.w)};
;                     f32x4 q0, q1;
;                     q0[0] = __builtin_amdgcn_rcpf(fmaxf(bflo(g.x), 1e-30f)); q0[1] = __builtin_amdgcn_rcpf(fmaxf(bfhi(g.x), 1e-30f)); q0[2] = __builtin_amdgcn_rcpf(fmaxf(bflo(g.y), 1e-30f)); q0[3] = __builtin_amdgcn_rcpf(fmaxf(bfhi(g.y), 1e-30f));
;                     q1[0] = __builtin_amdgcn_rcpf(fmaxf(bflo(g.z), 1e-30f)); q1[1] = __builtin_amdgcn_rcpf(fmaxf(bfhi(g.z), 1e-30f)); q1[2] = __builtin_amdgcn_rcpf(fmaxf(bflo(g.w), 1e-30f)); q1[3] = __builtin_amdgcn_rcpf(fmaxf(bfhi(g.w), 1e-30f));
;                     acc[ai][bj][m][0] = acc[ai][bj][m][0] * (r0 * q0); acc[ai][bj][m][1] = acc[ai][bj][m][1] * (r1 * q1);
;                 }
;             }
.LBB0_565:
	s_cmpk_lg_i32 s78, 0x1000
	s_cbranch_scc1 .LBB0_564
	v_mov_b32_e32 v4, v160
	s_mov_b64 s[80:81], 0x10000
	v_ashrrev_i32_e32 v5, 31, v4
	v_lshlrev_b64 v[4:5], 11, v[4:5]
	v_lshl_add_u64 v[4:5], v[4:5], 0, v[158:159]
	v_lshlrev_b64 v[4:5], 1, v[4:5]
	v_mov_b32_e32 v254, v4
	global_load_dwordx4 v[178:181], v254, s[12:13]
	global_load_dwordx4 v[182:185], v254, s[54:55]
	global_load_dwordx4 v[186:189], v254, s[12:13] offset:256
	global_load_dwordx4 v[190:193], v254, s[54:55] offset:256
	v_add_u32_e32 v165, 0x10000, v254
	global_load_dwordx4 v[194:197], v165, s[12:13]
	global_load_dwordx4 v[198:201], v165, s[54:55]
	v_add_u32_e32 v165, 0x10000, v254
	global_load_dwordx4 v[202:205], v165, s[12:13] offset:256
	global_load_dwordx4 v[206:209], v165, s[54:55] offset:256
	v_add_u32_e32 v165, 0x20000, v254
	global_load_dwordx4 v[210:213], v165, s[12:13]
	global_load_dwordx4 v[214:217], v165, s[54:55]
	v_add_u32_e32 v165, 0x20000, v254
	global_load_dwordx4 v[218:221], v165, s[12:13] offset:256
	global_load_dwordx4 v[222:225], v165, s[54:55] offset:256
	v_add_u32_e32 v165, 0x30000, v254
	global_load_dwordx4 v[226:229], v165, s[12:13]
	global_load_dwordx4 v[230:233], v165, s[54:55]
	v_add_u32_e32 v165, 0x30000, v254
	global_load_dwordx4 v[234:237], v165, s[12:13] offset:256
	global_load_dwordx4 v[238:241], v165, s[54:55] offset:256
	v_lshl_add_u64 v[134:135], s[12:13], 0, v[4:5]
	v_lshl_add_u64 v[136:137], s[54:55], 0, v[4:5]
	s_mov_b64 s[34:35], 0x20000
	s_waitcnt vmcnt(14)
	v_mov_b64_e32 v[138:139], v[178:179]
	v_mov_b64_e32 v[140:141], v[180:181]
	v_mov_b64_e32 v[166:167], v[182:183]
	v_mov_b64_e32 v[168:169], v[184:185]
	v_add_u32_e32 v165, 0x80000, v254
	global_load_dwordx4 v[178:181], v165, s[12:13]
	global_load_dwordx4 v[182:185], v165, s[54:55]
	v_lshlrev_b32_e32 v170, 16, v138
	v_lshlrev_b32_e32 v3, 16, v166
	v_max_f32_e32 v3, v3, v3
	v_max_f32_e32 v3, 0xda24260, v3
	v_rcp_f32_e32 v174, v3
	v_and_b32_e32 v3, 0xffff0000, v166
	v_max_f32_e32 v3, v3, v3
	v_max_f32_e32 v3, 0xda24260, v3
	v_rcp_f32_e32 v175, v3
	v_lshlrev_b32_e32 v3, 16, v167
	v_max_f32_e32 v3, v3, v3
	v_max_f32_e32 v3, 0xda24260, v3
	v_rcp_f32_e32 v166, v3
	v_and_b32_e32 v3, 0xffff0000, v167
	v_max_f32_e32 v3, v3, v3
	v_max_f32_e32 v3, 0xda24260, v3
	v_rcp_f32_e32 v167, v3
	v_lshlrev_b32_e32 v3, 16, v168
	v_max_f32_e32 v3, v3, v3
	v_max_f32_e32 v3, 0xda24260, v3
	v_rcp_f32_e32 v176, v3
	v_and_b32_e32 v3, 0xffff0000, v168
	v_max_f32_e32 v3, v3, v3
	v_max_f32_e32 v3, 0xda24260, v3
	v_rcp_f32_e32 v177, v3
	v_lshlrev_b32_e32 v3, 16, v169
	v_max_f32_e32 v3, v3, v3
	v_max_f32_e32 v3, 0xda24260, v3
	v_rcp_f32_e32 v168, v3
	v_and_b32_e32 v3, 0xffff0000, v169
	v_max_f32_e32 v3, v3, v3
	v_max_f32_e32 v3, 0xda24260, v3
	v_rcp_f32_e32 v169, v3
	v_and_b32_e32 v171, 0xffff0000, v138
	v_lshlrev_b32_e32 v138, 16, v139
	v_and_b32_e32 v139, 0xffff0000, v139
	v_lshlrev_b32_e32 v172, 16, v140
	v_and_b32_e32 v173, 0xffff0000, v140
	v_lshlrev_b32_e32 v140, 16, v141
	v_and_b32_e32 v141, 0xffff0000, v141
	v_pk_mul_f32 v[138:139], v[166:167], v[138:139]
	v_pk_mul_f32 v[140:141], v[168:169], v[140:141]
	v_pk_mul_f32 v[132:133], v[132:133], v[138:139]
	v_pk_mul_f32 v[138:139], v[176:177], v[172:173]
	v_pk_mul_f32 v[128:129], v[128:129], v[140:141]
	v_pk_mul_f32 v[126:127], v[126:127], v[138:139]
	s_nop 0
	v_pk_mul_f32 v[170:171], v[174:175], v[170:171]
	s_waitcnt vmcnt(14)
	v_mov_b64_e32 v[138:139], v[186:187]
	v_mov_b64_e32 v[140:141], v[188:189]
	v_mov_b64_e32 v[134:135], v[190:191]
	v_mov_b64_e32 v[136:137], v[192:193]
	v_add_u32_e32 v165, 0x80000, v254
	global_load_dwordx4 v[186:189], v165, s[12:13] offset:256
	global_load_dwordx4 v[190:193], v165, s[54:55] offset:256
	v_lshlrev_b32_e32 v166, 16, v138
	v_lshlrev_b32_e32 v3, 16, v134
	v_max_f32_e32 v3, v3, v3
	v_max_f32_e32 v3, 0xda24260, v3
	v_pk_mul_f32 v[130:131], v[130:131], v[170:171]
	v_rcp_f32_e32 v170, v3
	v_and_b32_e32 v3, 0xffff0000, v134
	v_max_f32_e32 v3, v3, v3
	v_max_f32_e32 v3, 0xda24260, v3
	v_rcp_f32_e32 v171, v3
	v_lshlrev_b32_e32 v3, 16, v135
	v_max_f32_e32 v3, v3, v3
	v_max_f32_e32 v3, 0xda24260, v3
	v_rcp_f32_e32 v134, v3
	v_and_b32_e32 v3, 0xffff0000, v135
	v_max_f32_e32 v3, v3, v3
	v_max_f32_e32 v3, 0xda24260, v3
	v_rcp_f32_e32 v135, v3
	v_lshlrev_b32_e32 v3, 16, v136
	v_max_f32_e32 v3, v3, v3
	v_max_f32_e32 v3, 0xda24260, v3
	v_rcp_f32_e32 v172, v3
	v_and_b32_e32 v3, 0xffff0000, v136
	v_max_f32_e32 v3, v3, v3
	v_max_f32_e32 v3, 0xda24260, v3
	v_rcp_f32_e32 v173, v3
	v_lshlrev_b32_e32 v3, 16, v137
	v_max_f32_e32 v3, v3, v3
	v_max_f32_e32 v3, 0xda24260, v3
	v_rcp_f32_e32 v136, v3
	v_and_b32_e32 v3, 0xffff0000, v137
	v_max_f32_e32 v3, v3, v3
	v_max_f32_e32 v3, 0xda24260, v3
	v_rcp_f32_e32 v137, v3
	v_and_b32_e32 v167, 0xffff0000, v138
	v_lshlrev_b32_e32 v138, 16, v139
	v_and_b32_e32 v139, 0xffff0000, v139
	v_lshlrev_b32_e32 v168, 16, v140
	v_and_b32_e32 v169, 0xffff0000, v140
	v_lshlrev_b32_e32 v140, 16, v141
	v_and_b32_e32 v141, 0xffff0000, v141
	v_pk_mul_f32 v[134:135], v[134:135], v[138:139]
	v_pk_mul_f32 v[136:137], v[136:137], v[140:141]
	v_pk_mul_f32 v[124:125], v[124:125], v[134:135]
	v_pk_mul_f32 v[134:135], v[172:173], v[168:169]
	v_pk_mul_f32 v[120:121], v[120:121], v[136:137]
	v_lshl_add_u64 v[136:137], v[4:5], 0, s[80:81]
	v_pk_mul_f32 v[166:167], v[170:171], v[166:167]
	v_pk_mul_f32 v[118:119], v[118:119], v[134:135]
	v_lshl_add_u64 v[134:135], s[12:13], 0, v[136:137]
	v_lshl_add_u64 v[138:139], s[54:55], 0, v[136:137]
	v_pk_mul_f32 v[122:123], v[122:123], v[166:167]
	s_waitcnt vmcnt(14)
;     __device__ __forceinline__ void mid(f32x4 (&acc)[2][2][4][2], const Unit& u, int wr, int wc, int fr, int fq) const {
;     ...
;                 const size_t off = (size_t)(row0 + ai * 128 + m * 16) * D + col0;
; #pragma unroll
;                 for (int bj = 0; bj < 2; ++bj) {
;                     const u32x4 r = *(const u32x4*)(GR + off + bj * 128), g = *(const u32x4*)(GA + off + bj * 128);
;                     const f32x4 r0 = (f32x4){bflo(r.x), bfhi(r.x), bflo(r.y), bfhi(r.y)}, r1 = (f32x4){bflo(r.z), bfhi(r.z), bflo(r.w), bfhi(r.w)};
;                     f32x4 q0, q1;
;                     q0[0] = __builtin_amdgcn_rcpf(fmaxf(bflo(g.x), 1e-30f)); q0[1] = __builtin_amdgcn_rcpf(fmaxf(bfhi(g.x), 1e-30f)); q0[2] = __builtin_amdgcn_rcpf(fmaxf(bflo(g.y), 1e-30f)); q0[3] = __builtin_amdgcn_rcpf(fmaxf(bfhi(g.y), 1e-30f));
;                     q1[0] = __builtin_amdgcn_rcpf(fmaxf(bflo(g.z), 1e-30f)); q1[1] = __builtin_amdgcn_rcpf(fmaxf(bfhi(g.z), 1e-30f)); q1[2] = __builtin_amdgcn_rcpf(fmaxf(bflo(g.w), 1e-30f)); q1[3] = __builtin_amdgcn_rcpf(fmaxf(bfhi(g.w), 1e-30f));
;                     acc[ai][bj][m][0] = acc[ai][bj][m][0] * (r0 * q0); acc[ai][bj][m][1] = acc[ai][bj][m][1] * (r1 * q1);
;                 }
	v_mov_b64_e32 v[166:167], v[194:195]
	v_mov_b64_e32 v[168:169], v[196:197]
	v_mov_b64_e32 v[170:171], v[198:199]
	v_mov_b64_e32 v[172:173], v[200:201]
	v_add_u32_e32 v165, 0x90000, v254
	global_load_dwordx4 v[194:197], v165, s[12:13]
	global_load_dwordx4 v[198:201], v165, s[54:55]
	v_lshlrev_b32_e32 v136, 16, v166
	v_lshlrev_b32_e32 v3, 16, v170
	v_max_f32_e32 v3, v3, v3
	v_max_f32_e32 v3, 0xda24260, v3
	v_rcp_f32_e32 v174, v3
	v_and_b32_e32 v3, 0xffff0000, v170
	v_max_f32_e32 v3, v3, v3
	v_max_f32_e32 v3, 0xda24260, v3
	v_rcp_f32_e32 v175, v3
	v_lshlrev_b32_e32 v3, 16, v171
	v_max_f32_e32 v3, v3, v3
	v_max_f32_e32 v3, 0xda24260, v3
	v_rcp_f32_e32 v170, v3
	v_and_b32_e32 v3, 0xffff0000, v171
	v_max_f32_e32 v3, v3, v3
	v_max_f32_e32 v3, 0xda24260, v3
	v_rcp_f32_e32 v171, v3
	v_lshlrev_b32_e32 v3, 16, v172
	v_max_f32_e32 v3, v3, v3
	v_max_f32_e32 v3, 0xda24260, v3
	v_rcp_f32_e32 v176, v3
	v_and_b32_e32 v3, 0xffff0000, v172
	v_max_f32_e32 v3, v3, v3
	v_max_f32_e32 v3, 0xda24260, v3
	v_rcp_f32_e32 v177, v3
	v_lshlrev_b32_e32 v3, 16, v173
	v_max_f32_e32 v3, v3, v3
	v_max_f32_e32 v3, 0xda24260, v3
	v_rcp_f32_e32 v172, v3
	v_and_b32_e32 v3, 0xffff0000, v173
	v_max_f32_e32 v3, v3, v3
	v_max_f32_e32 v3, 0xda24260, v3
	v_rcp_f32_e32 v173, v3
	v_and_b32_e32 v137, 0xffff0000, v166
	v_lshlrev_b32_e32 v140, 16, v167
	v_and_b32_e32 v141, 0xffff0000, v167
	v_lshlrev_b32_e32 v166, 16, v168
	v_and_b32_e32 v167, 0xffff0000, v168
	v_lshlrev_b32_e32 v168, 16, v169
	v_and_b32_e32 v169, 0xffff0000, v169
	v_pk_mul_f32 v[136:137], v[174:175], v[136:137]
	v_pk_mul_f32 v[140:141], v[170:171], v[140:141]
	v_pk_mul_f32 v[114:115], v[114:115], v[136:137]
	v_pk_mul_f32 v[116:117], v[116:117], v[140:141]
	v_pk_mul_f32 v[136:137], v[176:177], v[166:167]
	v_pk_mul_f32 v[140:141], v[172:173], v[168:169]
	v_pk_mul_f32 v[110:111], v[110:111], v[136:137]
	v_pk_mul_f32 v[112:113], v[112:113], v[140:141]
	s_nop 0
	s_waitcnt vmcnt(14)
	v_mov_b64_e32 v[134:135], v[202:203]
	v_mov_b64_e32 v[136:137], v[204:205]
	v_mov_b64_e32 v[138:139], v[206:207]
	v_mov_b64_e32 v[140:141], v[208:209]
	v_add_u32_e32 v165, 0x90000, v254
	global_load_dwordx4 v[202:205], v165, s[12:13] offset:256
	global_load_dwordx4 v[206:209], v165, s[54:55] offset:256
	v_lshlrev_b32_e32 v166, 16, v134
	v_lshlrev_b32_e32 v3, 16, v138
	v_max_f32_e32 v3, v3, v3
	v_max_f32_e32 v3, 0xda24260, v3
	v_rcp_f32_e32 v170, v3
	v_and_b32_e32 v3, 0xffff0000, v138
	v_max_f32_e32 v3, v3, v3
	v_max_f32_e32 v3, 0xda24260, v3
	v_rcp_f32_e32 v171, v3
	v_lshlrev_b32_e32 v3, 16, v139
	v_max_f32_e32 v3, v3, v3
	v_max_f32_e32 v3, 0xda24260, v3
	v_rcp_f32_e32 v138, v3
	v_and_b32_e32 v3, 0xffff0000, v139
	v_max_f32_e32 v3, v3, v3
	v_max_f32_e32 v3, 0xda24260, v3
	v_rcp_f32_e32 v139, v3
	v_lshlrev_b32_e32 v3, 16, v140
	v_max_f32_e32 v3, v3, v3
	v_max_f32_e32 v3, 0xda24260, v3
	v_rcp_f32_e32 v172, v3
	v_and_b32_e32 v3, 0xffff0000, v140
	v_max_f32_e32 v3, v3, v3
	v_max_f32_e32 v3, 0xda24260, v3
	v_rcp_f32_e32 v173, v3
	v_lshlrev_b32_e32 v3, 16, v141
	v_max_f32_e32 v3, v3, v3
	v_max_f32_e32 v3, 0xda24260, v3
	v_rcp_f32_e32 v140, v3
	v_and_b32_e32 v3, 0xffff0000, v141
	v_max_f32_e32 v3, v3, v3
	v_max_f32_e32 v3, 0xda24260, v3
	v_rcp_f32_e32 v141, v3
	v_and_b32_e32 v167, 0xffff0000, v134
	v_lshlrev_b32_e32 v134, 16, v135
	v_and_b32_e32 v135, 0xffff0000, v135
	v_lshlrev_b32_e32 v168, 16, v136
	v_and_b32_e32 v169, 0xffff0000, v136
	v_pk_mul_f32 v[134:135], v[138:139], v[134:135]
	v_lshlrev_b32_e32 v136, 16, v137
	v_and_b32_e32 v137, 0xffff0000, v137
	v_pk_mul_f32 v[108:109], v[108:109], v[134:135]
	v_pk_mul_f32 v[134:135], v[172:173], v[168:169]
	v_pk_mul_f32 v[136:137], v[140:141], v[136:137]
	v_pk_mul_f32 v[102:103], v[102:103], v[134:135]
	v_lshl_add_u64 v[134:135], v[4:5], 0, s[34:35]
	v_pk_mul_f32 v[166:167], v[170:171], v[166:167]
	v_pk_mul_f32 v[104:105], v[104:105], v[136:137]
	v_lshl_add_u64 v[136:137], s[12:13], 0, v[134:135]
	v_lshl_add_u64 v[134:135], s[54:55], 0, v[134:135]
	v_pk_mul_f32 v[106:107], v[106:107], v[166:167]
	s_mov_b64 s[34:35], 0x30000
	s_waitcnt vmcnt(14)
	v_mov_b64_e32 v[138:139], v[210:211]
	v_mov_b64_e32 v[140:141], v[212:213]
	v_mov_b64_e32 v[166:167], v[214:215]
	v_mov_b64_e32 v[168:169], v[216:217]
	v_add_u32_e32 v165, 0xa0000, v254
	global_load_dwordx4 v[210:213], v165, s[12:13]
	global_load_dwordx4 v[214:217], v165, s[54:55]
	v_lshlrev_b32_e32 v170, 16, v138
	v_lshlrev_b32_e32 v3, 16, v166
	v_max_f32_e32 v3, v3, v3
	v_max_f32_e32 v3, 0xda24260, v3
	v_rcp_f32_e32 v174, v3
	v_and_b32_e32 v3, 0xffff0000, v166
	v_max_f32_e32 v3, v3, v3
	v_max_f32_e32 v3, 0xda24260, v3
	v_rcp_f32_e32 v175, v3
	v_lshlrev_b32_e32 v3, 16, v167
	v_max_f32_e32 v3, v3, v3
	v_max_f32_e32 v3, 0xda24260, v3
	v_rcp_f32_e32 v166, v3
	v_and_b32_e32 v3, 0xffff0000, v167
	v_max_f32_e32 v3, v3, v3
	v_max_f32_e32 v3, 0xda24260, v3
	v_rcp_f32_e32 v167, v3
	v_lshlrev_b32_e32 v3, 16, v168
	v_max_f32_e32 v3, v3, v3
	v_max_f32_e32 v3, 0xda24260, v3
	v_rcp_f32_e32 v176, v3
	v_and_b32_e32 v3, 0xffff0000, v168
	v_max_f32_e32 v3, v3, v3
	v_max_f32_e32 v3, 0xda24260, v3
	v_rcp_f32_e32 v177, v3
	v_lshlrev_b32_e32 v3, 16, v169
	v_max_f32_e32 v3, v3, v3
	v_max_f32_e32 v3, 0xda24260, v3
	v_rcp_f32_e32 v168, v3
	v_and_b32_e32 v3, 0xffff0000, v169
	v_max_f32_e32 v3, v3, v3
	v_max_f32_e32 v3, 0xda24260, v3
	v_rcp_f32_e32 v169, v3
	v_and_b32_e32 v171, 0xffff0000, v138
	v_lshlrev_b32_e32 v138, 16, v139
	v_and_b32_e32 v139, 0xffff0000, v139
	v_lshlrev_b32_e32 v172, 16, v140
	v_and_b32_e32 v173, 0xffff0000, v140
	v_pk_mul_f32 v[138:139], v[166:167], v[138:139]
	v_lshlrev_b32_e32 v140, 16, v141
	v_and_b32_e32 v141, 0xffff0000, v141
	v_pk_mul_f32 v[100:101], v[100:101], v[138:139]
	v_pk_mul_f32 v[138:139], v[176:177], v[172:173]
	v_pk_mul_f32 v[140:141], v[168:169], v[140:141]
	v_pk_mul_f32 v[94:95], v[94:95], v[138:139]
	s_nop 0
	v_pk_mul_f32 v[170:171], v[174:175], v[170:171]
	v_pk_mul_f32 v[96:97], v[96:97], v[140:141]
	v_pk_mul_f32 v[98:99], v[98:99], v[170:171]
	s_waitcnt vmcnt(14)
;     __device__ __forceinline__ void mid(f32x4 (&acc)[2][2][4][2], const Unit& u, int wr, int wc, int fr, int fq) const {
;     ...
;                 const size_t off = (size_t)(row0 + ai * 128 + m * 16) * D + col0;
; #pragma unroll
;                 for (int bj = 0; bj < 2; ++bj) {
;                     const u32x4 r = *(const u32x4*)(GR + off + bj * 128), g = *(const u32x4*)(GA + off + bj * 128);
;                     const f32x4 r0 = (f32x4){bflo(r.x), bfhi(r.x), bflo(r.y), bfhi(r.y)}, r1 = (f32x4){bflo(r.z), bfhi(r.z), bflo(r.w), bfhi(r.w)};
;                     f32x4 q0, q1;
;                     q0[0] = __builtin_amdgcn_rcpf(fmaxf(bflo(g.x), 1e-30f)); q0[1] = __builtin_amdgcn_rcpf(fmaxf(bfhi(g.x), 1e-30f)); q0[2] = __builtin_amdgcn_rcpf(fmaxf(bflo(g.y), 1e-30f)); q0[3] = __builtin_amdgcn_rcpf(fmaxf(bfhi(g.y), 1e-30f));
;                     q1[0] = __builtin_amdgcn_rcpf(fmaxf(bflo(g.z), 1e-30f)); q1[1] = __builtin_amdgcn_rcpf(fmaxf(bfhi(g.z), 1e-30f)); q1[2] = __builtin_amdgcn_rcpf(fmaxf(bflo(g.w), 1e-30f)); q1[3] = __builtin_amdgcn_rcpf(fmaxf(bfhi(g.w), 1e-30f));
;                     acc[ai][bj][m][0] = acc[ai][bj][m][0] * (r0 * q0); acc[ai][bj][m][1] = acc[ai][bj][m][1] * (r1 * q1);
;                 }
	v_mov_b64_e32 v[136:137], v[218:219]
	v_mov_b64_e32 v[138:139], v[220:221]
	v_mov_b64_e32 v[166:167], v[222:223]
	v_mov_b64_e32 v[168:169], v[224:225]
	v_add_u32_e32 v165, 0xa0000, v254
	global_load_dwordx4 v[218:221], v165, s[12:13] offset:256
	global_load_dwordx4 v[222:225], v165, s[54:55] offset:256
	v_lshlrev_b32_e32 v134, 16, v136
	v_lshlrev_b32_e32 v3, 16, v166
	v_max_f32_e32 v3, v3, v3
	v_max_f32_e32 v3, 0xda24260, v3
	v_rcp_f32_e32 v170, v3
	v_and_b32_e32 v3, 0xffff0000, v166
	v_max_f32_e32 v3, v3, v3
	v_max_f32_e32 v3, 0xda24260, v3
	v_rcp_f32_e32 v171, v3
	v_lshlrev_b32_e32 v3, 16, v167
	v_max_f32_e32 v3, v3, v3
	v_max_f32_e32 v3, 0xda24260, v3
	v_rcp_f32_e32 v166, v3
	v_and_b32_e32 v3, 0xffff0000, v167
	v_max_f32_e32 v3, v3, v3
	v_max_f32_e32 v3, 0xda24260, v3
	v_rcp_f32_e32 v167, v3
	v_lshlrev_b32_e32 v3, 16, v168
	v_max_f32_e32 v3, v3, v3
	v_max_f32_e32 v3, 0xda24260, v3
	v_rcp_f32_e32 v172, v3
	v_and_b32_e32 v3, 0xffff0000, v168
	v_max_f32_e32 v3, v3, v3
	v_max_f32_e32 v3, 0xda24260, v3
	v_rcp_f32_e32 v173, v3
	v_lshlrev_b32_e32 v3, 16, v169
	v_max_f32_e32 v3, v3, v3
	v_max_f32_e32 v3, 0xda24260, v3
	v_rcp_f32_e32 v168, v3
	v_and_b32_e32 v3, 0xffff0000, v169
	v_max_f32_e32 v3, v3, v3
	v_max_f32_e32 v3, 0xda24260, v3
	v_rcp_f32_e32 v169, v3
	v_and_b32_e32 v135, 0xffff0000, v136
	v_lshlrev_b32_e32 v136, 16, v137
	v_and_b32_e32 v137, 0xffff0000, v137
	v_lshlrev_b32_e32 v140, 16, v138
	v_and_b32_e32 v141, 0xffff0000, v138
	v_pk_mul_f32 v[134:135], v[170:171], v[134:135]
	v_lshlrev_b32_e32 v138, 16, v139
	v_and_b32_e32 v139, 0xffff0000, v139
	v_pk_mul_f32 v[136:137], v[166:167], v[136:137]
	v_pk_mul_f32 v[90:91], v[90:91], v[134:135]
	v_pk_mul_f32 v[134:135], v[172:173], v[140:141]
	v_pk_mul_f32 v[92:93], v[92:93], v[136:137]
	v_pk_mul_f32 v[136:137], v[168:169], v[138:139]
	v_pk_mul_f32 v[86:87], v[86:87], v[134:135]
	v_lshl_add_u64 v[134:135], v[4:5], 0, s[34:35]
	v_pk_mul_f32 v[88:89], v[88:89], v[136:137]
	v_lshl_add_u64 v[136:137], s[12:13], 0, v[134:135]
	v_lshl_add_u64 v[134:135], s[54:55], 0, v[134:135]
	s_waitcnt vmcnt(14)
	v_mov_b64_e32 v[138:139], v[226:227]
	v_mov_b64_e32 v[140:141], v[228:229]
	v_mov_b64_e32 v[166:167], v[230:231]
	v_mov_b64_e32 v[168:169], v[232:233]
	v_add_u32_e32 v165, 0xb0000, v254
	global_load_dwordx4 v[226:229], v165, s[12:13]
	global_load_dwordx4 v[230:233], v165, s[54:55]
	v_lshlrev_b32_e32 v170, 16, v138
	v_lshlrev_b32_e32 v3, 16, v166
	v_max_f32_e32 v3, v3, v3
	v_max_f32_e32 v3, 0xda24260, v3
	v_rcp_f32_e32 v174, v3
	v_and_b32_e32 v3, 0xffff0000, v166
	v_max_f32_e32 v3, v3, v3
	v_max_f32_e32 v3, 0xda24260, v3
	v_rcp_f32_e32 v175, v3
	v_lshlrev_b32_e32 v3, 16, v167
	v_max_f32_e32 v3, v3, v3
	v_max_f32_e32 v3, 0xda24260, v3
	v_rcp_f32_e32 v166, v3
	v_and_b32_e32 v3, 0xffff0000, v167
	v_max_f32_e32 v3, v3, v3
	v_max_f32_e32 v3, 0xda24260, v3
	v_rcp_f32_e32 v167, v3
	v_lshlrev_b32_e32 v3, 16, v168
	v_max_f32_e32 v3, v3, v3
	v_max_f32_e32 v3, 0xda24260, v3
	v_rcp_f32_e32 v176, v3
	v_and_b32_e32 v3, 0xffff0000, v168
	v_max_f32_e32 v3, v3, v3
	v_max_f32_e32 v3, 0xda24260, v3
	v_rcp_f32_e32 v177, v3
	v_lshlrev_b32_e32 v3, 16, v169
	v_max_f32_e32 v3, v3, v3
	v_max_f32_e32 v3, 0xda24260, v3
	v_rcp_f32_e32 v168, v3
	v_and_b32_e32 v3, 0xffff0000, v169
	v_max_f32_e32 v3, v3, v3
	v_max_f32_e32 v3, 0xda24260, v3
	v_rcp_f32_e32 v169, v3
	v_and_b32_e32 v171, 0xffff0000, v138
	v_lshlrev_b32_e32 v138, 16, v139
	v_and_b32_e32 v139, 0xffff0000, v139
	v_lshlrev_b32_e32 v172, 16, v140
	v_and_b32_e32 v173, 0xffff0000, v140
	v_pk_mul_f32 v[138:139], v[166:167], v[138:139]
	v_lshlrev_b32_e32 v140, 16, v141
	v_and_b32_e32 v141, 0xffff0000, v141
	v_pk_mul_f32 v[84:85], v[84:85], v[138:139]
	v_pk_mul_f32 v[138:139], v[176:177], v[172:173]
	v_pk_mul_f32 v[140:141], v[168:169], v[140:141]
	v_pk_mul_f32 v[78:79], v[78:79], v[138:139]
	s_nop 0
	v_pk_mul_f32 v[170:171], v[174:175], v[170:171]
	v_pk_mul_f32 v[80:81], v[80:81], v[140:141]
	v_pk_mul_f32 v[82:83], v[82:83], v[170:171]
	s_waitcnt vmcnt(14)
	v_mov_b64_e32 v[136:137], v[234:235]
	v_mov_b64_e32 v[138:139], v[236:237]
	v_mov_b64_e32 v[166:167], v[238:239]
	v_mov_b64_e32 v[168:169], v[240:241]
	v_add_u32_e32 v165, 0xb0000, v254
	global_load_dwordx4 v[234:237], v165, s[12:13] offset:256
	global_load_dwordx4 v[238:241], v165, s[54:55] offset:256
	v_lshlrev_b32_e32 v134, 16, v136
	v_lshlrev_b32_e32 v3, 16, v166
	v_max_f32_e32 v3, v3, v3
	v_max_f32_e32 v3, 0xda24260, v3
	v_rcp_f32_e32 v170, v3
	v_and_b32_e32 v3, 0xffff0000, v166
	v_max_f32_e32 v3, v3, v3
	v_max_f32_e32 v3, 0xda24260, v3
	v_rcp_f32_e32 v171, v3
	v_lshlrev_b32_e32 v3, 16, v167
	v_max_f32_e32 v3, v3, v3
	v_max_f32_e32 v3, 0xda24260, v3
	v_rcp_f32_e32 v166, v3
	v_and_b32_e32 v3, 0xffff0000, v167
	v_max_f32_e32 v3, v3, v3
	v_max_f32_e32 v3, 0xda24260, v3
	v_rcp_f32_e32 v167, v3
	v_lshlrev_b32_e32 v3, 16, v168
	v_max_f32_e32 v3, v3, v3
	v_max_f32_e32 v3, 0xda24260, v3
	v_rcp_f32_e32 v172, v3
	v_and_b32_e32 v3, 0xffff0000, v168
	v_max_f32_e32 v3, v3, v3
	v_max_f32_e32 v3, 0xda24260, v3
	v_rcp_f32_e32 v173, v3
	v_lshlrev_b32_e32 v3, 16, v169
	v_max_f32_e32 v3, v3, v3
	v_max_f32_e32 v3, 0xda24260, v3
	v_rcp_f32_e32 v168, v3
	v_and_b32_e32 v3, 0xffff0000, v169
	v_max_f32_e32 v3, v3, v3
	v_max_f32_e32 v3, 0xda24260, v3
	v_rcp_f32_e32 v169, v3
	v_and_b32_e32 v135, 0xffff0000, v136
	v_lshlrev_b32_e32 v136, 16, v137
	v_and_b32_e32 v137, 0xffff0000, v137
	v_lshlrev_b32_e32 v140, 16, v138
	v_and_b32_e32 v141, 0xffff0000, v138
	v_pk_mul_f32 v[134:135], v[170:171], v[134:135]
	v_lshlrev_b32_e32 v138, 16, v139
	v_and_b32_e32 v139, 0xffff0000, v139
	v_pk_mul_f32 v[136:137], v[166:167], v[136:137]
	v_pk_mul_f32 v[74:75], v[74:75], v[134:135]
	v_pk_mul_f32 v[134:135], v[172:173], v[140:141]
	v_pk_mul_f32 v[76:77], v[76:77], v[136:137]
	v_pk_mul_f32 v[136:137], v[168:169], v[138:139]
	v_pk_mul_f32 v[70:71], v[70:71], v[134:135]
	v_lshl_add_u64 v[134:135], v[4:5], 0, s[50:51]
	v_pk_mul_f32 v[72:73], v[72:73], v[136:137]
	v_lshl_add_u64 v[136:137], s[12:13], 0, v[134:135]
	v_lshl_add_u64 v[134:135], s[54:55], 0, v[134:135]
	s_waitcnt vmcnt(14)
;     __device__ __forceinline__ void mid(f32x4 (&acc)[2][2][4][2], const Unit& u, int wr, int wc, int fr, int fq) const {
;     ...
;                 const size_t off = (size_t)(row0 + ai * 128 + m * 16) * D + col0;
; #pragma unroll
;                 for (int bj = 0; bj < 2; ++bj) {
;                     const u32x4 r = *(const u32x4*)(GR + off + bj * 128), g = *(const u32x4*)(GA + off + bj * 128);
;                     const f32x4 r0 = (f32x4){bflo(r.x), bfhi(r.x), bflo(r.y), bfhi(r.y)}, r1 = (f32x4){bflo(r.z), bfhi(r.z), bflo(r.w), bfhi(r.w)};
;                     f32x4 q0, q1;
;                     q0[0] = __builtin_amdgcn_rcpf(fmaxf(bflo(g.x), 1e-30f)); q0[1] = __builtin_amdgcn_rcpf(fmaxf(bfhi(g.x), 1e-30f)); q0[2] = __builtin_amdgcn_rcpf(fmaxf(bflo(g.y), 1e-30f)); q0[3] = __builtin_amdgcn_rcpf(fmaxf(bfhi(g.y), 1e-30f));
;                     q1[0] = __builtin_amdgcn_rcpf(fmaxf(bflo(g.z), 1e-30f)); q1[1] = __builtin_amdgcn_rcpf(fmaxf(bfhi(g.z), 1e-30f)); q1[2] = __builtin_amdgcn_rcpf(fmaxf(bflo(g.w), 1e-30f)); q1[3] = __builtin_amdgcn_rcpf(fmaxf(bfhi(g.w), 1e-30f));
;                     acc[ai][bj][m][0] = acc[ai][bj][m][0] * (r0 * q0); acc[ai][bj][m][1] = acc[ai][bj][m][1] * (r1 * q1);
;                 }
	v_mov_b64_e32 v[138:139], v[178:179]
	v_mov_b64_e32 v[140:141], v[180:181]
	v_mov_b64_e32 v[166:167], v[182:183]
	v_mov_b64_e32 v[168:169], v[184:185]
	v_lshlrev_b32_e32 v170, 16, v138
	v_lshlrev_b32_e32 v3, 16, v166
	v_max_f32_e32 v3, v3, v3
	v_max_f32_e32 v3, 0xda24260, v3
	v_rcp_f32_e32 v174, v3
	v_and_b32_e32 v3, 0xffff0000, v166
	v_max_f32_e32 v3, v3, v3
	v_max_f32_e32 v3, 0xda24260, v3
	v_rcp_f32_e32 v175, v3
	v_lshlrev_b32_e32 v3, 16, v167
	v_max_f32_e32 v3, v3, v3
	v_max_f32_e32 v3, 0xda24260, v3
	v_rcp_f32_e32 v166, v3
	v_and_b32_e32 v3, 0xffff0000, v167
	v_max_f32_e32 v3, v3, v3
	v_max_f32_e32 v3, 0xda24260, v3
	v_rcp_f32_e32 v167, v3
	v_lshlrev_b32_e32 v3, 16, v168
	v_max_f32_e32 v3, v3, v3
	v_max_f32_e32 v3, 0xda24260, v3
	v_rcp_f32_e32 v176, v3
	v_and_b32_e32 v3, 0xffff0000, v168
	v_max_f32_e32 v3, v3, v3
	v_max_f32_e32 v3, 0xda24260, v3
	v_rcp_f32_e32 v177, v3
	v_lshlrev_b32_e32 v3, 16, v169
	v_max_f32_e32 v3, v3, v3
	v_max_f32_e32 v3, 0xda24260, v3
	v_rcp_f32_e32 v168, v3
	v_and_b32_e32 v3, 0xffff0000, v169
	v_max_f32_e32 v3, v3, v3
	v_max_f32_e32 v3, 0xda24260, v3
	v_rcp_f32_e32 v169, v3
	v_and_b32_e32 v171, 0xffff0000, v138
	v_lshlrev_b32_e32 v138, 16, v139
	v_and_b32_e32 v139, 0xffff0000, v139
	v_lshlrev_b32_e32 v172, 16, v140
	v_and_b32_e32 v173, 0xffff0000, v140
	v_pk_mul_f32 v[138:139], v[166:167], v[138:139]
	v_lshlrev_b32_e32 v140, 16, v141
	v_and_b32_e32 v141, 0xffff0000, v141
	v_pk_mul_f32 v[68:69], v[68:69], v[138:139]
	v_pk_mul_f32 v[138:139], v[176:177], v[172:173]
	v_pk_mul_f32 v[140:141], v[168:169], v[140:141]
	v_pk_mul_f32 v[62:63], v[62:63], v[138:139]
	s_nop 0
	v_pk_mul_f32 v[170:171], v[174:175], v[170:171]
	v_pk_mul_f32 v[64:65], v[64:65], v[140:141]
	v_pk_mul_f32 v[66:67], v[66:67], v[170:171]
	s_waitcnt vmcnt(12)
	v_mov_b64_e32 v[136:137], v[186:187]
	v_mov_b64_e32 v[138:139], v[188:189]
	v_mov_b64_e32 v[166:167], v[190:191]
	v_mov_b64_e32 v[168:169], v[192:193]
	v_lshlrev_b32_e32 v134, 16, v136
	v_lshlrev_b32_e32 v3, 16, v166
	v_max_f32_e32 v3, v3, v3
	v_max_f32_e32 v3, 0xda24260, v3
	v_rcp_f32_e32 v170, v3
	v_and_b32_e32 v3, 0xffff0000, v166
	v_max_f32_e32 v3, v3, v3
	v_max_f32_e32 v3, 0xda24260, v3
	v_rcp_f32_e32 v171, v3
	v_lshlrev_b32_e32 v3, 16, v167
	v_max_f32_e32 v3, v3, v3
	v_max_f32_e32 v3, 0xda24260, v3
	v_rcp_f32_e32 v166, v3
	v_and_b32_e32 v3, 0xffff0000, v167
	v_max_f32_e32 v3, v3, v3
	v_max_f32_e32 v3, 0xda24260, v3
	v_rcp_f32_e32 v167, v3
	v_lshlrev_b32_e32 v3, 16, v168
	v_max_f32_e32 v3, v3, v3
	v_max_f32_e32 v3, 0xda24260, v3
	v_rcp_f32_e32 v172, v3
	v_and_b32_e32 v3, 0xffff0000, v168
	v_max_f32_e32 v3, v3, v3
	v_max_f32_e32 v3, 0xda24260, v3
	v_rcp_f32_e32 v173, v3
	v_lshlrev_b32_e32 v3, 16, v169
	v_max_f32_e32 v3, v3, v3
	v_max_f32_e32 v3, 0xda24260, v3
	v_rcp_f32_e32 v168, v3
	v_and_b32_e32 v3, 0xffff0000, v169
	v_max_f32_e32 v3, v3, v3
	v_max_f32_e32 v3, 0xda24260, v3
	v_rcp_f32_e32 v169, v3
	v_and_b32_e32 v135, 0xffff0000, v136
	v_lshlrev_b32_e32 v136, 16, v137
	v_and_b32_e32 v137, 0xffff0000, v137
	v_lshlrev_b32_e32 v140, 16, v138
	v_and_b32_e32 v141, 0xffff0000, v138
	v_pk_mul_f32 v[134:135], v[170:171], v[134:135]
	v_lshlrev_b32_e32 v138, 16, v139
	v_and_b32_e32 v139, 0xffff0000, v139
	v_pk_mul_f32 v[136:137], v[166:167], v[136:137]
	v_pk_mul_f32 v[58:59], v[58:59], v[134:135]
	v_pk_mul_f32 v[134:135], v[172:173], v[140:141]
	v_pk_mul_f32 v[60:61], v[60:61], v[136:137]
	v_pk_mul_f32 v[136:137], v[168:169], v[138:139]
	v_pk_mul_f32 v[54:55], v[54:55], v[134:135]
	v_lshl_add_u64 v[134:135], v[4:5], 0, s[60:61]
	v_pk_mul_f32 v[56:57], v[56:57], v[136:137]
	v_lshl_add_u64 v[136:137], s[12:13], 0, v[134:135]
	v_lshl_add_u64 v[134:135], s[54:55], 0, v[134:135]
	s_waitcnt vmcnt(10)
	v_mov_b64_e32 v[138:139], v[194:195]
	v_mov_b64_e32 v[140:141], v[196:197]
	v_mov_b64_e32 v[166:167], v[198:199]
	v_mov_b64_e32 v[168:169], v[200:201]
	v_lshlrev_b32_e32 v170, 16, v138
	v_lshlrev_b32_e32 v3, 16, v166
	v_max_f32_e32 v3, v3, v3
	v_max_f32_e32 v3, 0xda24260, v3
	v_rcp_f32_e32 v174, v3
	v_and_b32_e32 v3, 0xffff0000, v166
	v_max_f32_e32 v3, v3, v3
	v_max_f32_e32 v3, 0xda24260, v3
	v_rcp_f32_e32 v175, v3
	v_lshlrev_b32_e32 v3, 16, v167
	v_max_f32_e32 v3, v3, v3
	v_max_f32_e32 v3, 0xda24260, v3
	v_rcp_f32_e32 v166, v3
	v_and_b32_e32 v3, 0xffff0000, v167
	v_max_f32_e32 v3, v3, v3
	v_max_f32_e32 v3, 0xda24260, v3
	v_rcp_f32_e32 v167, v3
	v_lshlrev_b32_e32 v3, 16, v168
	v_max_f32_e32 v3, v3, v3
	v_max_f32_e32 v3, 0xda24260, v3
	v_rcp_f32_e32 v176, v3
	v_and_b32_e32 v3, 0xffff0000, v168
	v_max_f32_e32 v3, v3, v3
	v_max_f32_e32 v3, 0xda24260, v3
	v_rcp_f32_e32 v177, v3
	v_lshlrev_b32_e32 v3, 16, v169
	v_max_f32_e32 v3, v3, v3
	v_max_f32_e32 v3, 0xda24260, v3
	v_rcp_f32_e32 v168, v3
	v_and_b32_e32 v3, 0xffff0000, v169
	v_max_f32_e32 v3, v3, v3
	v_max_f32_e32 v3, 0xda24260, v3
	v_rcp_f32_e32 v169, v3
	v_and_b32_e32 v171, 0xffff0000, v138
	v_lshlrev_b32_e32 v138, 16, v139
	v_and_b32_e32 v139, 0xffff0000, v139
	v_lshlrev_b32_e32 v172, 16, v140
	v_and_b32_e32 v173, 0xffff0000, v140
	v_pk_mul_f32 v[138:139], v[166:167], v[138:139]
	v_lshlrev_b32_e32 v140, 16, v141
	v_and_b32_e32 v141, 0xffff0000, v141
	v_pk_mul_f32 v[52:53], v[52:53], v[138:139]
	v_pk_mul_f32 v[138:139], v[176:177], v[172:173]
	v_pk_mul_f32 v[140:141], v[168:169], v[140:141]
	v_pk_mul_f32 v[46:47], v[46:47], v[138:139]
	s_nop 0
	v_pk_mul_f32 v[170:171], v[174:175], v[170:171]
	v_pk_mul_f32 v[48:49], v[48:49], v[140:141]
	v_pk_mul_f32 v[50:51], v[50:51], v[170:171]
	s_waitcnt vmcnt(8)
;     __device__ __forceinline__ void mid(f32x4 (&acc)[2][2][4][2], const Unit& u, int wr, int wc, int fr, int fq) const {
;     ...
;                 const size_t off = (size_t)(row0 + ai * 128 + m * 16) * D + col0;
; #pragma unroll
;                 for (int bj = 0; bj < 2; ++bj) {
;                     const u32x4 r = *(const u32x4*)(GR + off + bj * 128), g = *(const u32x4*)(GA + off + bj * 128);
;                     const f32x4 r0 = (f32x4){bflo(r.x), bfhi(r.x), bflo(r.y), bfhi(r.y)}, r1 = (f32x4){bflo(r.z), bfhi(r.z), bflo(r.w), bfhi(r.w)};
;                     f32x4 q0, q1;
;                     q0[0] = __builtin_amdgcn_rcpf(fmaxf(bflo(g.x), 1e-30f)); q0[1] = __builtin_amdgcn_rcpf(fmaxf(bfhi(g.x), 1e-30f)); q0[2] = __builtin_amdgcn_rcpf(fmaxf(bflo(g.y), 1e-30f)); q0[3] = __builtin_amdgcn_rcpf(fmaxf(bfhi(g.y), 1e-30f));
;                     q1[0] = __builtin_amdgcn_rcpf(fmaxf(bflo(g.z), 1e-30f)); q1[1] = __builtin_amdgcn_rcpf(fmaxf(bfhi(g.z), 1e-30f)); q1[2] = __builtin_amdgcn_rcpf(fmaxf(bflo(g.w), 1e-30f)); q1[3] = __builtin_amdgcn_rcpf(fmaxf(bfhi(g.w), 1e-30f));
;                     acc[ai][bj][m][0] = acc[ai][bj][m][0] * (r0 * q0); acc[ai][bj][m][1] = acc[ai][bj][m][1] * (r1 * q1);
;                 }
	v_mov_b64_e32 v[136:137], v[202:203]
	v_mov_b64_e32 v[138:139], v[204:205]
	v_mov_b64_e32 v[166:167], v[206:207]
	v_mov_b64_e32 v[168:169], v[208:209]
	v_lshlrev_b32_e32 v134, 16, v136
	v_lshlrev_b32_e32 v3, 16, v166
	v_max_f32_e32 v3, v3, v3
	v_max_f32_e32 v3, 0xda24260, v3
	v_rcp_f32_e32 v170, v3
	v_and_b32_e32 v3, 0xffff0000, v166
	v_max_f32_e32 v3, v3, v3
	v_max_f32_e32 v3, 0xda24260, v3
	v_rcp_f32_e32 v171, v3
	v_lshlrev_b32_e32 v3, 16, v167
	v_max_f32_e32 v3, v3, v3
	v_max_f32_e32 v3, 0xda24260, v3
	v_rcp_f32_e32 v166, v3
	v_and_b32_e32 v3, 0xffff0000, v167
	v_max_f32_e32 v3, v3, v3
	v_max_f32_e32 v3, 0xda24260, v3
	v_rcp_f32_e32 v167, v3
	v_lshlrev_b32_e32 v3, 16, v168
	v_max_f32_e32 v3, v3, v3
	v_max_f32_e32 v3, 0xda24260, v3
	v_rcp_f32_e32 v172, v3
	v_and_b32_e32 v3, 0xffff0000, v168
	v_max_f32_e32 v3, v3, v3
	v_max_f32_e32 v3, 0xda24260, v3
	v_rcp_f32_e32 v173, v3
	v_lshlrev_b32_e32 v3, 16, v169
	v_max_f32_e32 v3, v3, v3
	v_max_f32_e32 v3, 0xda24260, v3
	v_rcp_f32_e32 v168, v3
	v_and_b32_e32 v3, 0xffff0000, v169
	v_max_f32_e32 v3, v3, v3
	v_max_f32_e32 v3, 0xda24260, v3
	v_rcp_f32_e32 v169, v3
	v_and_b32_e32 v135, 0xffff0000, v136
	v_lshlrev_b32_e32 v136, 16, v137
	v_and_b32_e32 v137, 0xffff0000, v137
	v_lshlrev_b32_e32 v140, 16, v138
	v_and_b32_e32 v141, 0xffff0000, v138
	v_pk_mul_f32 v[134:135], v[170:171], v[134:135]
	v_lshlrev_b32_e32 v138, 16, v139
	v_and_b32_e32 v139, 0xffff0000, v139
	v_pk_mul_f32 v[136:137], v[166:167], v[136:137]
	v_pk_mul_f32 v[42:43], v[42:43], v[134:135]
	v_pk_mul_f32 v[134:135], v[172:173], v[140:141]
	v_pk_mul_f32 v[44:45], v[44:45], v[136:137]
	v_pk_mul_f32 v[136:137], v[168:169], v[138:139]
	v_pk_mul_f32 v[38:39], v[38:39], v[134:135]
	v_lshl_add_u64 v[134:135], v[4:5], 0, s[62:63]
	v_pk_mul_f32 v[40:41], v[40:41], v[136:137]
	v_lshl_add_u64 v[136:137], s[12:13], 0, v[134:135]
	v_lshl_add_u64 v[134:135], s[54:55], 0, v[134:135]
	v_lshl_add_u64 v[4:5], v[4:5], 0, s[64:65]
	s_waitcnt vmcnt(6)
	v_mov_b64_e32 v[138:139], v[210:211]
	v_mov_b64_e32 v[140:141], v[212:213]
	v_mov_b64_e32 v[166:167], v[214:215]
	v_mov_b64_e32 v[168:169], v[216:217]
	v_lshlrev_b32_e32 v170, 16, v138
	v_lshlrev_b32_e32 v3, 16, v166
	v_max_f32_e32 v3, v3, v3
	v_max_f32_e32 v3, 0xda24260, v3
	v_rcp_f32_e32 v174, v3
	v_and_b32_e32 v3, 0xffff0000, v166
	v_max_f32_e32 v3, v3, v3
	v_max_f32_e32 v3, 0xda24260, v3
	v_rcp_f32_e32 v175, v3
	v_lshlrev_b32_e32 v3, 16, v167
	v_max_f32_e32 v3, v3, v3
	v_max_f32_e32 v3, 0xda24260, v3
	v_rcp_f32_e32 v166, v3
	v_and_b32_e32 v3, 0xffff0000, v167
	v_max_f32_e32 v3, v3, v3
	v_max_f32_e32 v3, 0xda24260, v3
	v_rcp_f32_e32 v167, v3
	v_lshlrev_b32_e32 v3, 16, v168
	v_max_f32_e32 v3, v3, v3
	v_max_f32_e32 v3, 0xda24260, v3
	v_rcp_f32_e32 v176, v3
	v_and_b32_e32 v3, 0xffff0000, v168
	v_max_f32_e32 v3, v3, v3
	v_max_f32_e32 v3, 0xda24260, v3
	v_rcp_f32_e32 v177, v3
	v_lshlrev_b32_e32 v3, 16, v169
	v_max_f32_e32 v3, v3, v3
	v_max_f32_e32 v3, 0xda24260, v3
	v_rcp_f32_e32 v168, v3
	v_and_b32_e32 v3, 0xffff0000, v169
	v_max_f32_e32 v3, v3, v3
	v_max_f32_e32 v3, 0xda24260, v3
	v_rcp_f32_e32 v169, v3
	v_and_b32_e32 v171, 0xffff0000, v138
	v_lshlrev_b32_e32 v138, 16, v139
	v_and_b32_e32 v139, 0xffff0000, v139
	v_lshlrev_b32_e32 v172, 16, v140
	v_and_b32_e32 v173, 0xffff0000, v140
	v_pk_mul_f32 v[138:139], v[166:167], v[138:139]
	v_lshlrev_b32_e32 v140, 16, v141
	v_and_b32_e32 v141, 0xffff0000, v141
	v_pk_mul_f32 v[36:37], v[36:37], v[138:139]
	v_pk_mul_f32 v[138:139], v[176:177], v[172:173]
	v_pk_mul_f32 v[140:141], v[168:169], v[140:141]
	v_pk_mul_f32 v[30:31], v[30:31], v[138:139]
	s_nop 0
	v_pk_mul_f32 v[170:171], v[174:175], v[170:171]
	v_pk_mul_f32 v[32:33], v[32:33], v[140:141]
	v_pk_mul_f32 v[34:35], v[34:35], v[170:171]
	s_waitcnt vmcnt(4)
;     __device__ __forceinline__ void mid(f32x4 (&acc)[2][2][4][2], const Unit& u, int wr, int wc, int fr, int fq) const {
;     ...
;                 const size_t off = (size_t)(row0 + ai * 128 + m * 16) * D + col0;
; #pragma unroll
;                 for (int bj = 0; bj < 2; ++bj) {
;                     const u32x4 r = *(const u32x4*)(GR + off + bj * 128), g = *(const u32x4*)(GA + off + bj * 128);
;                     const f32x4 r0 = (f32x4){bflo(r.x), bfhi(r.x), bflo(r.y), bfhi(r.y)}, r1 = (f32x4){bflo(r.z), bfhi(r.z), bflo(r.w), bfhi(r.w)};
;                     f32x4 q0, q1;
;                     q0[0] = __builtin_amdgcn_rcpf(fmaxf(bflo(g.x), 1e-30f)); q0[1] = __builtin_amdgcn_rcpf(fmaxf(bfhi(g.x), 1e-30f)); q0[2] = __builtin_amdgcn_rcpf(fmaxf(bflo(g.y), 1e-30f)); q0[3] = __builtin_amdgcn_rcpf(fmaxf(bfhi(g.y), 1e-30f));
;                     q1[0] = __builtin_amdgcn_rcpf(fmaxf(bflo(g.z), 1e-30f)); q1[1] = __builtin_amdgcn_rcpf(fmaxf(bfhi(g.z), 1e-30f)); q1[2] = __builtin_amdgcn_rcpf(fmaxf(bflo(g.w), 1e-30f)); q1[3] = __builtin_amdgcn_rcpf(fmaxf(bfhi(g.w), 1e-30f));
;                     acc[ai][bj][m][0] = acc[ai][bj][m][0] * (r0 * q0); acc[ai][bj][m][1] = acc[ai][bj][m][1] * (r1 * q1);
;                 }
	v_mov_b64_e32 v[136:137], v[218:219]
	v_mov_b64_e32 v[138:139], v[220:221]
	v_mov_b64_e32 v[166:167], v[222:223]
	v_mov_b64_e32 v[168:169], v[224:225]
	v_lshlrev_b32_e32 v134, 16, v136
	v_lshlrev_b32_e32 v3, 16, v166
	v_max_f32_e32 v3, v3, v3
	v_max_f32_e32 v3, 0xda24260, v3
	v_rcp_f32_e32 v170, v3
	v_and_b32_e32 v3, 0xffff0000, v166
	v_max_f32_e32 v3, v3, v3
	v_max_f32_e32 v3, 0xda24260, v3
	v_rcp_f32_e32 v171, v3
	v_lshlrev_b32_e32 v3, 16, v167
	v_max_f32_e32 v3, v3, v3
	v_max_f32_e32 v3, 0xda24260, v3
	v_rcp_f32_e32 v166, v3
	v_and_b32_e32 v3, 0xffff0000, v167
	v_max_f32_e32 v3, v3, v3
	v_max_f32_e32 v3, 0xda24260, v3
	v_rcp_f32_e32 v167, v3
	v_lshlrev_b32_e32 v3, 16, v168
	v_max_f32_e32 v3, v3, v3
	v_max_f32_e32 v3, 0xda24260, v3
	v_rcp_f32_e32 v172, v3
	v_and_b32_e32 v3, 0xffff0000, v168
	v_max_f32_e32 v3, v3, v3
	v_max_f32_e32 v3, 0xda24260, v3
	v_rcp_f32_e32 v173, v3
	v_lshlrev_b32_e32 v3, 16, v169
	v_max_f32_e32 v3, v3, v3
	v_max_f32_e32 v3, 0xda24260, v3
	v_rcp_f32_e32 v168, v3
	v_and_b32_e32 v3, 0xffff0000, v169
	v_max_f32_e32 v3, v3, v3
	v_max_f32_e32 v3, 0xda24260, v3
	v_rcp_f32_e32 v169, v3
	v_and_b32_e32 v135, 0xffff0000, v136
	v_lshlrev_b32_e32 v136, 16, v137
	v_and_b32_e32 v137, 0xffff0000, v137
	v_lshlrev_b32_e32 v140, 16, v138
	v_and_b32_e32 v141, 0xffff0000, v138
	v_pk_mul_f32 v[134:135], v[170:171], v[134:135]
	v_lshlrev_b32_e32 v138, 16, v139
	v_and_b32_e32 v139, 0xffff0000, v139
	v_pk_mul_f32 v[136:137], v[166:167], v[136:137]
	v_pk_mul_f32 v[26:27], v[26:27], v[134:135]
	v_pk_mul_f32 v[134:135], v[172:173], v[140:141]
	v_pk_mul_f32 v[28:29], v[28:29], v[136:137]
	v_pk_mul_f32 v[136:137], v[168:169], v[138:139]
	v_pk_mul_f32 v[22:23], v[22:23], v[134:135]
	v_lshl_add_u64 v[134:135], s[12:13], 0, v[4:5]
	v_lshl_add_u64 v[4:5], s[54:55], 0, v[4:5]
	v_pk_mul_f32 v[24:25], v[24:25], v[136:137]
	s_waitcnt vmcnt(2)
	v_mov_b64_e32 v[136:137], v[226:227]
	v_mov_b64_e32 v[138:139], v[228:229]
	v_mov_b64_e32 v[166:167], v[230:231]
	v_mov_b64_e32 v[168:169], v[232:233]
	v_lshlrev_b32_e32 v140, 16, v136
	v_lshlrev_b32_e32 v3, 16, v166
	v_max_f32_e32 v3, v3, v3
	v_max_f32_e32 v3, 0xda24260, v3
	v_rcp_f32_e32 v172, v3
	v_and_b32_e32 v3, 0xffff0000, v166
	v_max_f32_e32 v3, v3, v3
	v_max_f32_e32 v3, 0xda24260, v3
	v_rcp_f32_e32 v173, v3
	v_lshlrev_b32_e32 v3, 16, v167
	v_max_f32_e32 v3, v3, v3
	v_max_f32_e32 v3, 0xda24260, v3
	v_rcp_f32_e32 v166, v3
	v_and_b32_e32 v3, 0xffff0000, v167
	v_max_f32_e32 v3, v3, v3
	v_max_f32_e32 v3, 0xda24260, v3
	v_rcp_f32_e32 v167, v3
	v_lshlrev_b32_e32 v3, 16, v168
	v_max_f32_e32 v3, v3, v3
	v_max_f32_e32 v3, 0xda24260, v3
	v_rcp_f32_e32 v174, v3
	v_and_b32_e32 v3, 0xffff0000, v168
	v_max_f32_e32 v3, v3, v3
	v_max_f32_e32 v3, 0xda24260, v3
	v_rcp_f32_e32 v175, v3
	v_lshlrev_b32_e32 v3, 16, v169
	v_max_f32_e32 v3, v3, v3
	v_max_f32_e32 v3, 0xda24260, v3
	v_rcp_f32_e32 v168, v3
	v_and_b32_e32 v3, 0xffff0000, v169
	v_max_f32_e32 v3, v3, v3
	v_max_f32_e32 v3, 0xda24260, v3
	v_rcp_f32_e32 v169, v3
	v_and_b32_e32 v141, 0xffff0000, v136
	v_lshlrev_b32_e32 v136, 16, v137
	v_and_b32_e32 v137, 0xffff0000, v137
	v_lshlrev_b32_e32 v170, 16, v138
	v_and_b32_e32 v171, 0xffff0000, v138
	v_lshlrev_b32_e32 v138, 16, v139
	v_and_b32_e32 v139, 0xffff0000, v139
	v_pk_mul_f32 v[136:137], v[166:167], v[136:137]
	v_pk_mul_f32 v[140:141], v[172:173], v[140:141]
	v_pk_mul_f32 v[20:21], v[20:21], v[136:137]
	v_pk_mul_f32 v[136:137], v[174:175], v[170:171]
	v_pk_mul_f32 v[138:139], v[168:169], v[138:139]
	v_pk_mul_f32 v[18:19], v[18:19], v[140:141]
	v_pk_mul_f32 v[16:17], v[16:17], v[138:139]
	v_pk_mul_f32 v[14:15], v[14:15], v[136:137]
	s_nop 0
	s_waitcnt vmcnt(0)
	v_mov_b64_e32 v[134:135], v[234:235]
	v_mov_b64_e32 v[136:137], v[236:237]
	v_mov_b64_e32 v[138:139], v[238:239]
	v_mov_b64_e32 v[140:141], v[240:241]
	v_lshlrev_b32_e32 v4, 16, v134
	v_lshlrev_b32_e32 v3, 16, v138
	v_max_f32_e32 v3, v3, v3
	v_max_f32_e32 v3, 0xda24260, v3
	v_rcp_f32_e32 v168, v3
	v_and_b32_e32 v3, 0xffff0000, v138
	v_max_f32_e32 v3, v3, v3
	v_max_f32_e32 v3, 0xda24260, v3
	v_rcp_f32_e32 v169, v3
	v_lshlrev_b32_e32 v3, 16, v139
	v_max_f32_e32 v3, v3, v3
	v_max_f32_e32 v3, 0xda24260, v3
	v_rcp_f32_e32 v138, v3
	v_and_b32_e32 v3, 0xffff0000, v139
	v_max_f32_e32 v3, v3, v3
	v_max_f32_e32 v3, 0xda24260, v3
	v_rcp_f32_e32 v139, v3
	v_lshlrev_b32_e32 v3, 16, v140
	v_max_f32_e32 v3, v3, v3
	v_max_f32_e32 v3, 0xda24260, v3
	v_rcp_f32_e32 v170, v3
	v_and_b32_e32 v3, 0xffff0000, v140
	v_max_f32_e32 v3, v3, v3
	v_max_f32_e32 v3, 0xda24260, v3
	v_rcp_f32_e32 v171, v3
	v_lshlrev_b32_e32 v3, 16, v141
	v_max_f32_e32 v3, v3, v3
	v_max_f32_e32 v3, 0xda24260, v3
	v_rcp_f32_e32 v140, v3
	v_and_b32_e32 v3, 0xffff0000, v141
	v_max_f32_e32 v3, v3, v3
	v_max_f32_e32 v3, 0xda24260, v3
	v_rcp_f32_e32 v141, v3
	v_and_b32_e32 v5, 0xffff0000, v134
	v_lshlrev_b32_e32 v134, 16, v135
	v_and_b32_e32 v135, 0xffff0000, v135
	v_lshlrev_b32_e32 v166, 16, v136
	v_and_b32_e32 v167, 0xffff0000, v136
	v_lshlrev_b32_e32 v136, 16, v137
	v_and_b32_e32 v137, 0xffff0000, v137
	v_pk_mul_f32 v[4:5], v[168:169], v[4:5]
	v_pk_mul_f32 v[134:135], v[138:139], v[134:135]
	v_pk_mul_f32 v[10:11], v[10:11], v[4:5]
	v_pk_mul_f32 v[12:13], v[12:13], v[134:135]
	v_pk_mul_f32 v[4:5], v[170:171], v[166:167]
	v_pk_mul_f32 v[134:135], v[140:141], v[136:137]
	v_pk_mul_f32 v[6:7], v[6:7], v[4:5]
	v_pk_mul_f32 v[8:9], v[8:9], v[134:135]
	s_branch .LBB0_564

;     __device__ __forceinline__ void operator()(const f32x4 (&acc)[2][2][4][2], const Unit& u, int wr, int wc, int fr, int fq) const {
;         const int row0 = u.pm * 256 + wr * 64 + fr, col0 = u.pn * 256 + wc * 32 + 4 * fq;
; #pragma unroll
;         for (int ai = 0; ai < 2; ++ai)
; #pragma unroll
;             for (int m = 0; m < 4; ++m) {
;                 const size_t off = (size_t)(row0 + ai * 128 + m * 16) * D + col0;
; #pragma unroll
;                 for (int bj = 0; bj < 2; ++bj)
; #pragma unroll
;                     for (int n = 0; n < 2; ++n) { const f32x4 b = *(const f32x4*)(base + off + bj * 128 + n * 16); *(f32x4*)(out + off + bj * 128 + n * 16) = b + acc[ai][bj][m][n]; }
;             }
;     }
.LBB0_1093:
	v_lshl_add_u32 v146, s73, 8, v1
	v_lshl_or_b32 v142, s74, 8, v149
	v_lshlrev_b32_e32 v143, 13, v146
	v_lshl_add_u32 v143, v142, 2, v143
	v_add_u32_e32 v147, 0x20000, v143
	v_add_u32_e32 v248, 0x40000, v143
	v_add_u32_e32 v249, 0x60000, v143
	v_add_u32_e32 v250, 0x100000, v143
	v_add_u32_e32 v251, 0x120000, v143
	v_add_u32_e32 v252, 0x140000, v143
	v_add_u32_e32 v253, 0x160000, v143
	global_load_dwordx4 v[160:163], v143, s[12:13]
	global_load_dwordx4 v[164:167], v143, s[12:13] offset:64
	global_load_dwordx4 v[168:171], v143, s[12:13] offset:512
	global_load_dwordx4 v[172:175], v143, s[12:13] offset:576
	global_load_dwordx4 v[176:179], v147, s[12:13]
	global_load_dwordx4 v[180:183], v147, s[12:13] offset:64
	global_load_dwordx4 v[184:187], v147, s[12:13] offset:512
	global_load_dwordx4 v[188:191], v147, s[12:13] offset:576
	global_load_dwordx4 v[192:195], v248, s[12:13]
	global_load_dwordx4 v[196:199], v248, s[12:13] offset:64
	global_load_dwordx4 v[200:203], v248, s[12:13] offset:512
	global_load_dwordx4 v[204:207], v248, s[12:13] offset:576
	global_load_dwordx4 v[208:211], v249, s[12:13]
	global_load_dwordx4 v[212:215], v249, s[12:13] offset:64
	global_load_dwordx4 v[216:219], v249, s[12:13] offset:512
	global_load_dwordx4 v[220:223], v249, s[12:13] offset:576
	s_waitcnt vmcnt(12)
	v_pk_add_f32 v[126:127], v[126:127], v[160:161]
	v_pk_add_f32 v[128:129], v[128:129], v[162:163]
	v_pk_add_f32 v[122:123], v[122:123], v[164:165]
	v_pk_add_f32 v[124:125], v[124:125], v[166:167]
	v_pk_add_f32 v[118:119], v[118:119], v[168:169]
	v_pk_add_f32 v[120:121], v[120:121], v[170:171]
	v_pk_add_f32 v[110:111], v[110:111], v[172:173]
	v_pk_add_f32 v[112:113], v[112:113], v[174:175]
	global_load_dwordx4 v[160:163], v250, s[12:13]
	global_load_dwordx4 v[164:167], v250, s[12:13] offset:64
	global_load_dwordx4 v[168:171], v250, s[12:13] offset:512
	global_load_dwordx4 v[172:175], v250, s[12:13] offset:576
	s_waitcnt vmcnt(12)
	v_pk_add_f32 v[114:115], v[114:115], v[176:177]
	v_pk_add_f32 v[116:117], v[116:117], v[178:179]
	v_pk_add_f32 v[106:107], v[106:107], v[180:181]
	v_pk_add_f32 v[108:109], v[108:109], v[182:183]
	v_pk_add_f32 v[102:103], v[102:103], v[184:185]
	v_pk_add_f32 v[104:105], v[104:105], v[186:187]
	v_pk_add_f32 v[98:99], v[98:99], v[188:189]
	v_pk_add_f32 v[100:101], v[100:101], v[190:191]
	global_load_dwordx4 v[176:179], v251, s[12:13]
	global_load_dwordx4 v[180:183], v251, s[12:13] offset:64
	global_load_dwordx4 v[184:187], v251, s[12:13] offset:512
	global_load_dwordx4 v[188:191], v251, s[12:13] offset:576
	s_waitcnt vmcnt(12)
	v_pk_add_f32 v[94:95], v[94:95], v[192:193]
	v_pk_add_f32 v[96:97], v[96:97], v[194:195]
	v_pk_add_f32 v[90:91], v[90:91], v[196:197]
	v_pk_add_f32 v[92:93], v[92:93], v[198:199]
	v_pk_add_f32 v[86:87], v[86:87], v[200:201]
	v_pk_add_f32 v[88:89], v[88:89], v[202:203]
	v_pk_add_f32 v[82:83], v[82:83], v[204:205]
	v_pk_add_f32 v[84:85], v[84:85], v[206:207]
	global_load_dwordx4 v[192:195], v252, s[12:13]
	global_load_dwordx4 v[196:199], v252, s[12:13] offset:64
	global_load_dwordx4 v[200:203], v252, s[12:13] offset:512
	global_load_dwordx4 v[204:207], v252, s[12:13] offset:576
	s_waitcnt vmcnt(12)
;     __device__ __forceinline__ void operator()(const f32x4 (&acc)[2][2][4][2], const Unit& u, int wr, int wc, int fr, int fq) const {
;         const int row0 = u.pm * 256 + wr * 64 + fr, col0 = u.pn * 256 + wc * 32 + 4 * fq;
; #pragma unroll
;         for (int ai = 0; ai < 2; ++ai)
; #pragma unroll
;             for (int m = 0; m < 4; ++m) {
;                 const size_t off = (size_t)(row0 + ai * 128 + m * 16) * D + col0;
; #pragma unroll
;                 for (int bj = 0; bj < 2; ++bj)
; #pragma unroll
;                     for (int n = 0; n < 2; ++n) { const f32x4 b = *(const f32x4*)(base + off + bj * 128 + n * 16); *(f32x4*)(out + off + bj * 128 + n * 16) = b + acc[ai][bj][m][n]; }
;             }
;     }
	v_pk_add_f32 v[78:79], v[78:79], v[208:209]
	v_pk_add_f32 v[80:81], v[80:81], v[210:211]
	v_pk_add_f32 v[74:75], v[74:75], v[212:213]
	v_pk_add_f32 v[76:77], v[76:77], v[214:215]
	v_pk_add_f32 v[70:71], v[70:71], v[216:217]
	v_pk_add_f32 v[72:73], v[72:73], v[218:219]
	v_pk_add_f32 v[66:67], v[66:67], v[220:221]
	v_pk_add_f32 v[68:69], v[68:69], v[222:223]
	global_load_dwordx4 v[208:211], v253, s[12:13]
	global_load_dwordx4 v[212:215], v253, s[12:13] offset:64
	global_load_dwordx4 v[216:219], v253, s[12:13] offset:512
	global_load_dwordx4 v[220:223], v253, s[12:13] offset:576
	global_store_dwordx4 v143, v[126:129], s[12:13]
	global_store_dwordx4 v143, v[122:125], s[12:13] offset:64
	global_store_dwordx4 v143, v[118:121], s[12:13] offset:512
	global_store_dwordx4 v143, v[110:113], s[12:13] offset:576
	global_store_dwordx4 v147, v[114:117], s[12:13]
	global_store_dwordx4 v147, v[106:109], s[12:13] offset:64
	global_store_dwordx4 v147, v[102:105], s[12:13] offset:512
	global_store_dwordx4 v147, v[98:101], s[12:13] offset:576
	global_store_dwordx4 v248, v[94:97], s[12:13]
	global_store_dwordx4 v248, v[90:93], s[12:13] offset:64
	global_store_dwordx4 v248, v[86:89], s[12:13] offset:512
	global_store_dwordx4 v248, v[82:85], s[12:13] offset:576
	global_store_dwordx4 v249, v[78:81], s[12:13]
	global_store_dwordx4 v249, v[74:77], s[12:13] offset:64
	global_store_dwordx4 v249, v[70:73], s[12:13] offset:512
	global_store_dwordx4 v249, v[66:69], s[12:13] offset:576
	s_waitcnt vmcnt(12)
	v_pk_add_f32 v[62:63], v[62:63], v[160:161]
	v_pk_add_f32 v[64:65], v[64:65], v[162:163]
	v_pk_add_f32 v[58:59], v[58:59], v[164:165]
	v_pk_add_f32 v[60:61], v[60:61], v[166:167]
	v_pk_add_f32 v[54:55], v[54:55], v[168:169]
	v_pk_add_f32 v[56:57], v[56:57], v[170:171]
	v_pk_add_f32 v[50:51], v[50:51], v[172:173]
	v_pk_add_f32 v[52:53], v[52:53], v[174:175]
	s_waitcnt vmcnt(8)
	v_pk_add_f32 v[46:47], v[46:47], v[176:177]
	v_pk_add_f32 v[48:49], v[48:49], v[178:179]
	v_pk_add_f32 v[42:43], v[42:43], v[180:181]
	v_pk_add_f32 v[44:45], v[44:45], v[182:183]
	v_pk_add_f32 v[38:39], v[38:39], v[184:185]
	v_pk_add_f32 v[40:41], v[40:41], v[186:187]
	v_pk_add_f32 v[34:35], v[34:35], v[188:189]
	v_pk_add_f32 v[36:37], v[36:37], v[190:191]
	s_waitcnt vmcnt(4)
	v_pk_add_f32 v[30:31], v[30:31], v[192:193]
	v_pk_add_f32 v[32:33], v[32:33], v[194:195]
	v_pk_add_f32 v[26:27], v[26:27], v[196:197]
	v_pk_add_f32 v[28:29], v[28:29], v[198:199]
	v_pk_add_f32 v[22:23], v[22:23], v[200:201]
	v_pk_add_f32 v[24:25], v[24:25], v[202:203]
	v_pk_add_f32 v[18:19], v[18:19], v[204:205]
	v_pk_add_f32 v[20:21], v[20:21], v[206:207]
	s_waitcnt vmcnt(0)
	v_pk_add_f32 v[14:15], v[14:15], v[208:209]
	v_pk_add_f32 v[16:17], v[16:17], v[210:211]
	v_pk_add_f32 v[10:11], v[10:11], v[212:213]
	v_pk_add_f32 v[12:13], v[12:13], v[214:215]
	v_pk_add_f32 v[6:7], v[6:7], v[216:217]
	v_pk_add_f32 v[8:9], v[8:9], v[218:219]
	v_pk_add_f32 v[2:3], v[2:3], v[220:221]
	v_pk_add_f32 v[4:5], v[4:5], v[222:223]
	global_store_dwordx4 v250, v[62:65], s[12:13]
	global_store_dwordx4 v250, v[58:61], s[12:13] offset:64
	global_store_dwordx4 v250, v[54:57], s[12:13] offset:512
	global_store_dwordx4 v250, v[50:53], s[12:13] offset:576
	global_store_dwordx4 v251, v[46:49], s[12:13]
	global_store_dwordx4 v251, v[42:45], s[12:13] offset:64
	global_store_dwordx4 v251, v[38:41], s[12:13] offset:512
	global_store_dwordx4 v251, v[34:37], s[12:13] offset:576
	global_store_dwordx4 v252, v[30:33], s[12:13]
	global_store_dwordx4 v252, v[26:29], s[12:13] offset:64
	global_store_dwordx4 v252, v[22:25], s[12:13] offset:512
	global_store_dwordx4 v252, v[18:21], s[12:13] offset:576
	global_store_dwordx4 v253, v[14:17], s[12:13]
	global_store_dwordx4 v253, v[10:13], s[12:13] offset:64
	global_store_dwordx4 v253, v[6:9], s[12:13] offset:512
	global_store_dwordx4 v253, v[2:5], s[12:13] offset:576
	s_mov_b64 s[48:49], -1
	s_and_b64 vcc, exec, s[2:3]
	s_cbranch_vccnz .LBB0_1078
	s_andn2_b64 vcc, exec, s[30:31]
	s_cbranch_vccnz .LBB0_1077
	s_barrier
	s_branch .LBB0_1077
